# attention tile loop: QK^T of second half before P.V of first, V^T reads two MFMAs ahead, cross-half row max via v_permlane32_swap; conv skipped on the 32 workgroups that carry an extra attention unit
# speedup vs baseline: 1.0011x; 1.0011x over previous
; __device__ __forceinline__ void attn_unit(LAS unsigned char* lds, const bf16_t* Q, const bf16_t* Kb, const bf16_t* Vb, bf16_t* O, const float* sink,
;                                           int qrow0, int kvh, int crow0, int lrow0, int jlo, int jhi, int qpos0, const int wave_s) {
;     ...
;         for (int qs = 0; qs < 2; ++qs) {
;             f32x16 S[2];
; #pragma unroll
;             for (int kt = 0; kt < 2; ++kt) {
; #pragma unroll
;                 for (int r = 0; r < 16; ++r) S[kt][r] = 0.f;
; #pragma unroll
;                 for (int ks = 0; ks < 4; ++ks) S[kt] = __builtin_amdgcn_mfma_f32_32x32x16_bf16(Kf[kt][ks], Qf[qs][ks], S[kt], 0, 0, 0);
;             }
;             if (masked) {
;                 const int qp = qpos0 + 32 * qs + l31;
; #pragma unroll
;                 for (int kt = 0; kt < 2; ++kt)
; #pragma unroll
;                     for (int r = 0; r < 16; ++r) { const int dlt = kp0 + 32 * kt + (r & 3) + 8 * (r >> 2) + 4 * h - qp; if (dlt > 128 || dlt < -128) S[kt][r] = -INFINITY; }
;             }
;             float mx = S[0][0];
; #pragma unroll
;             for (int kt = 0; kt < 2; ++kt)
; #pragma unroll
;                 for (int r = 0; r < 16; ++r) mx = fmaxf(mx, S[kt][r]);
;             mx = fmaxf(mx, xor_lane(mx, lane, 32));
;             const float mnew = fmaxf(mrow[qs], mx);
;             const float alpha = __builtin_amdgcn_exp2f(mrow[qs] - mnew);
;             mrow[qs] = mnew;
;             float ps = 0.f;
; #pragma unroll
;             for (int kt = 0; kt < 2; ++kt)
; #pragma unroll
;                 for (int r = 0; r < 16; ++r) { S[kt][r] = __builtin_amdgcn_exp2f(S[kt][r] - mnew); ps += S[kt][r]; }
;             lsum[qs] = lsum[qs] * alpha + ps;
; #pragma unroll
;             for (int dh = 0; dh < 2; ++dh)
; #pragma unroll
;                 for (int r = 0; r < 16; ++r) Oacc[qs][dh][r] *= alpha;
; #pragma unroll
;             for (int s = 0; s < 4; ++s) {
;                 const int kt = s >> 1, sp = s & 1;
;                 u32x4 pw; pw.x = cvt_pk_bf16(S[kt][8 * sp + 0], S[kt][8 * sp + 1]); pw.y = cvt_pk_bf16(S[kt][8 * sp + 2], S[kt][8 * sp + 3]);
;                 pw.z = cvt_pk_bf16(S[kt][8 * sp + 4], S[kt][8 * sp + 5]); pw.w = cvt_pk_bf16(S[kt][8 * sp + 6], S[kt][8 * sp + 7]);
;                 const bf16x8 Pf = __builtin_bit_cast(bf16x8, pw);
; #pragma unroll
;                 for (int dh = 0; dh < 2; ++dh) {
.LBB0_355:
	s_nop 8
	v_max_f32_e32 v179, v81, v81
	v_max_f32_e32 v180, v80, v80
	v_max_f32_e32 v179, v180, v179
	v_max3_f32 v179, v179, v82, v83
	v_max3_f32 v179, v179, v84, v85
	v_max3_f32 v179, v179, v86, v87
	v_max3_f32 v179, v179, v88, v89
	v_max3_f32 v179, v179, v90, v91
	v_max3_f32 v179, v179, v92, v93
	v_max3_f32 v179, v179, v94, v95
	v_max3_f32 v179, v179, v64, v65
	v_max3_f32 v179, v179, v66, v67
	v_max3_f32 v179, v179, v68, v69
	v_max3_f32 v179, v179, v70, v71
	v_max3_f32 v179, v179, v72, v73
	v_max3_f32 v179, v179, v74, v75
	v_max3_f32 v179, v179, v76, v77
	v_max3_f32 v179, v179, v78, v79
	v_add_u32_e32 v178, s31, v197
	v_mov_b32_e32 v180, v179
	v_add_u32_e32 v205, v178, v198
	s_andn2_b64 vcc, exec, s[12:13]
	s_nop 0
	v_permlane32_swap_b32_e32 v180, v179
	v_max3_f32 v203, v190, v179, v180
	v_sub_f32_e32 v64, v64, v203
	v_exp_f32_e32 v233, v64
	v_sub_f32_e32 v64, v65, v203
	v_exp_f32_e32 v234, v64
	v_sub_f32_e32 v64, v66, v203
	v_exp_f32_e32 v235, v64
	v_sub_f32_e32 v64, v67, v203
	v_exp_f32_e32 v236, v64
	v_sub_f32_e32 v64, v68, v203
	v_exp_f32_e32 v237, v64
	v_sub_f32_e32 v64, v69, v203
	v_exp_f32_e32 v238, v64
	v_sub_f32_e32 v64, v70, v203
	v_exp_f32_e32 v239, v64
	v_sub_f32_e32 v64, v71, v203
	v_sub_f32_e32 v80, v80, v203
	v_exp_f32_e32 v240, v64
	v_sub_f32_e32 v64, v72, v203
	v_exp_f32_e32 v206, v80
	v_sub_f32_e32 v80, v81, v203
	v_exp_f32_e32 v241, v64
	v_sub_f32_e32 v64, v73, v203
	v_exp_f32_e32 v209, v80
	v_sub_f32_e32 v80, v82, v203
	v_exp_f32_e32 v242, v64
	v_sub_f32_e32 v64, v74, v203
	v_exp_f32_e32 v211, v80
	v_sub_f32_e32 v80, v83, v203
	v_exp_f32_e32 v243, v64
	v_sub_f32_e32 v64, v75, v203
	v_exp_f32_e32 v213, v80
	v_sub_f32_e32 v80, v84, v203
	v_exp_f32_e32 v207, v64
	v_sub_f32_e32 v64, v76, v203
	v_exp_f32_e32 v215, v80
	v_sub_f32_e32 v80, v85, v203
	v_exp_f32_e32 v210, v64
	v_sub_f32_e32 v64, v77, v203
	v_exp_f32_e32 v222, v80
	v_sub_f32_e32 v80, v86, v203
	v_exp_f32_e32 v212, v64
	v_sub_f32_e32 v64, v78, v203
	v_sub_f32_e32 v179, v190, v203
	v_exp_f32_e32 v223, v80
	v_sub_f32_e32 v80, v87, v203
	v_exp_f32_e32 v214, v64
	v_sub_f32_e32 v64, v79, v203
	v_exp_f32_e32 v224, v80
	v_exp_f32_e32 v208, v64
	v_exp_f32_e32 v190, v179
	v_sub_f32_e32 v80, v88, v203
	v_exp_f32_e32 v225, v80
	v_sub_f32_e32 v80, v89, v203
	v_exp_f32_e32 v226, v80
	v_sub_f32_e32 v80, v90, v203
	v_pk_mul_f32 v[14:15], v[14:15], v[190:191] op_sel_hi:[1,0]
	v_pk_mul_f32 v[12:13], v[12:13], v[190:191] op_sel_hi:[1,0]
	v_pk_mul_f32 v[10:11], v[10:11], v[190:191] op_sel_hi:[1,0]
	v_pk_mul_f32 v[8:9], v[8:9], v[190:191] op_sel_hi:[1,0]
	v_pk_mul_f32 v[6:7], v[6:7], v[190:191] op_sel_hi:[1,0]
	v_pk_mul_f32 v[4:5], v[4:5], v[190:191] op_sel_hi:[1,0]
	v_pk_mul_f32 v[2:3], v[2:3], v[190:191] op_sel_hi:[1,0]
	v_pk_mul_f32 v[0:1], v[0:1], v[190:191] op_sel_hi:[1,0]
	v_exp_f32_e32 v227, v80
	v_sub_f32_e32 v80, v91, v203
	v_exp_f32_e32 v228, v80
	v_sub_f32_e32 v80, v92, v203
	v_exp_f32_e32 v229, v80
	v_sub_f32_e32 v80, v93, v203
	v_exp_f32_e32 v230, v80
	v_sub_f32_e32 v80, v94, v203
	v_exp_f32_e32 v231, v80
	v_sub_f32_e32 v80, v95, v203
	v_pk_mul_f32 v[62:63], v[62:63], v[190:191] op_sel_hi:[1,0]
	v_pk_mul_f32 v[60:61], v[60:61], v[190:191] op_sel_hi:[1,0]
	v_pk_mul_f32 v[58:59], v[58:59], v[190:191] op_sel_hi:[1,0]
	v_pk_mul_f32 v[56:57], v[56:57], v[190:191] op_sel_hi:[1,0]
	v_pk_mul_f32 v[54:55], v[54:55], v[190:191] op_sel_hi:[1,0]
	v_pk_mul_f32 v[52:53], v[52:53], v[190:191] op_sel_hi:[1,0]
	v_pk_mul_f32 v[50:51], v[50:51], v[190:191] op_sel_hi:[1,0]
	v_pk_mul_f32 v[48:49], v[48:49], v[190:191] op_sel_hi:[1,0]
	v_exp_f32_e32 v232, v80
	v_mfma_f32_32x32x16_bf16 v[80:95], v[140:143], v[112:115], 0
	v_mfma_f32_32x32x16_bf16 v[64:79], v[156:159], v[112:115], 0
	v_mfma_f32_32x32x16_bf16 v[80:95], v[136:139], v[116:119], v[80:95]
	v_mfma_f32_32x32x16_bf16 v[64:79], v[152:155], v[116:119], v[64:79]
	v_mfma_f32_32x32x16_bf16 v[80:95], v[148:151], v[120:123], v[80:95]
	v_mfma_f32_32x32x16_bf16 v[64:79], v[160:163], v[120:123], v[64:79]
	v_mfma_f32_32x32x16_bf16 v[80:95], v[144:147], v[124:127], v[80:95]
	v_mfma_f32_32x32x16_bf16 v[64:79], v[164:167], v[124:127], v[64:79]
	v_cvt_pk_bf16_f32 v136, v206, v209
	v_cvt_pk_bf16_f32 v137, v211, v213
	v_cvt_pk_bf16_f32 v138, v215, v222
	v_cvt_pk_bf16_f32 v139, v223, v224
	ds_read_b64_tr_b16 v[140:141], v205 offset:18432
	ds_read_b64_tr_b16 v[142:143], v205 offset:19968
	ds_read_b64_tr_b16 v[246:247], v205 offset:18496
	ds_read_b64_tr_b16 v[248:249], v205 offset:20032
	s_waitcnt lgkmcnt(2)
	v_mfma_f32_32x32x16_bf16 v[0:15], v[140:143], v[136:139], v[0:15]
	ds_read_b64_tr_b16 v[182:183], v205 offset:21504
	ds_read_b64_tr_b16 v[184:185], v205 offset:23040
	s_waitcnt lgkmcnt(2)
	v_mfma_f32_32x32x16_bf16 v[48:63], v[246:249], v[136:139], v[48:63]
	v_cvt_pk_bf16_f32 v136, v225, v226
	v_cvt_pk_bf16_f32 v137, v227, v228
	v_cvt_pk_bf16_f32 v138, v229, v230
	v_cvt_pk_bf16_f32 v139, v231, v232
	ds_read_b64_tr_b16 v[140:141], v205 offset:21568
	ds_read_b64_tr_b16 v[142:143], v205 offset:23104
	s_waitcnt lgkmcnt(2)
	v_mfma_f32_32x32x16_bf16 v[0:15], v[182:185], v[136:139], v[0:15]
	ds_read_b64_tr_b16 v[246:247], v205 offset:24576
	ds_read_b64_tr_b16 v[248:249], v205 offset:26112
	s_waitcnt lgkmcnt(2)
	v_mfma_f32_32x32x16_bf16 v[48:63], v[140:143], v[136:139], v[48:63]
	v_cvt_pk_bf16_f32 v136, v233, v234
	v_cvt_pk_bf16_f32 v137, v235, v236
	v_cvt_pk_bf16_f32 v138, v237, v238
	v_cvt_pk_bf16_f32 v139, v239, v240
	ds_read_b64_tr_b16 v[182:183], v205 offset:24640
	ds_read_b64_tr_b16 v[184:185], v205 offset:26176
	s_waitcnt lgkmcnt(2)
	v_mfma_f32_32x32x16_bf16 v[0:15], v[246:249], v[136:139], v[0:15]
	ds_read_b64_tr_b16 v[140:141], v205 offset:27648
	ds_read_b64_tr_b16 v[142:143], v205 offset:29184
	s_waitcnt lgkmcnt(2)
	v_mfma_f32_32x32x16_bf16 v[48:63], v[182:185], v[136:139], v[48:63]
	v_cvt_pk_bf16_f32 v136, v241, v242
	v_cvt_pk_bf16_f32 v137, v243, v207
	v_cvt_pk_bf16_f32 v138, v210, v212
	v_cvt_pk_bf16_f32 v139, v214, v208
	ds_read_b64_tr_b16 v[246:247], v205 offset:27712
	ds_read_b64_tr_b16 v[248:249], v205 offset:29248
	s_waitcnt lgkmcnt(2)
	v_mfma_f32_32x32x16_bf16 v[0:15], v[140:143], v[136:139], v[0:15]
	s_waitcnt lgkmcnt(0)
	v_mfma_f32_32x32x16_bf16 v[48:63], v[246:249], v[136:139], v[48:63]
	s_cbranch_vccnz .LBB0_357
; __device__ __forceinline__ float xor_lane(float v, int lane, int mask) { return __int_as_float(__builtin_amdgcn_ds_bpermute((lane ^ mask) << 2, __float_as_int(v))); }
; __device__ __forceinline__ void attn_unit(LAS unsigned char* lds, const bf16_t* Q, const bf16_t* Kb, const bf16_t* Vb, bf16_t* O, const float* sink,
;                                           int qrow0, int kvh, int crow0, int lrow0, int jlo, int jhi, int qpos0, const int wave_s) {
;     ...
;             if (masked) {
;                 const int qp = qpos0 + 32 * qs + l31;
; #pragma unroll
;                 for (int kt = 0; kt < 2; ++kt)
; #pragma unroll
;                     for (int r = 0; r < 16; ++r) { const int dlt = kp0 + 32 * kt + (r & 3) + 8 * (r >> 2) + 4 * h - qp; if (dlt > 128 || dlt < -128) S[kt][r] = -INFINITY; }
;             }
;             float mx = S[0][0];
; #pragma unroll
;             for (int kt = 0; kt < 2; ++kt)
; #pragma unroll
;                 for (int r = 0; r < 16; ++r) mx = fmaxf(mx, S[kt][r]);
;             mx = fmaxf(mx, xor_lane(mx, lane, 32));
;             const float mnew = fmaxf(mrow[qs], mx);
;             const float alpha = __builtin_amdgcn_exp2f(mrow[qs] - mnew);
;             mrow[qs] = mnew;
;             float ps = 0.f;
; #pragma unroll
;             for (int kt = 0; kt < 2; ++kt)
; #pragma unroll
;                 for (int r = 0; r < 16; ++r) { S[kt][r] = __builtin_amdgcn_exp2f(S[kt][r] - mnew); ps += S[kt][r]; }
;             lsum[qs] = lsum[qs] * alpha + ps;
	v_subrev_u32_e32 v136, 32, v204
	v_cmp_gt_u32_e32 vcc, s52, v136
	v_subrev_u32_e32 v136, 31, v204
	s_nop 6
	v_cndmask_b32_e32 v80, v80, v220, vcc
	v_cmp_lt_u32_e32 vcc, s89, v136
	v_subrev_u32_e32 v136, 30, v204
	s_nop 0
	v_cndmask_b32_e32 v81, v220, v81, vcc
	v_cmp_lt_u32_e32 vcc, s89, v136
	v_subrev_u32_e32 v136, 29, v204
	s_nop 0
	v_cndmask_b32_e32 v82, v220, v82, vcc
	v_cmp_lt_u32_e32 vcc, s89, v136
	v_subrev_u32_e32 v136, 24, v204
	s_nop 0
	v_cndmask_b32_e32 v83, v220, v83, vcc
	v_cmp_lt_u32_e32 vcc, s89, v136
	v_subrev_u32_e32 v136, 23, v204
	s_nop 0
	v_cndmask_b32_e32 v84, v220, v84, vcc
	v_cmp_lt_u32_e32 vcc, s89, v136
	v_subrev_u32_e32 v136, 22, v204
	s_nop 0
	v_cndmask_b32_e32 v85, v220, v85, vcc
	v_cmp_lt_u32_e32 vcc, s89, v136
	v_subrev_u32_e32 v136, 21, v204
	s_nop 0
	v_cndmask_b32_e32 v86, v220, v86, vcc
	v_cmp_lt_u32_e32 vcc, s89, v136
	v_add_u32_e32 v136, -16, v204
	s_nop 0
	v_cndmask_b32_e32 v87, v220, v87, vcc
	v_cmp_lt_u32_e32 vcc, s89, v136
	v_add_u32_e32 v136, -15, v204
	s_nop 0
	v_cndmask_b32_e32 v88, v220, v88, vcc
	v_cmp_lt_u32_e32 vcc, s89, v136
	v_add_u32_e32 v136, -14, v204
	s_nop 0
	v_cndmask_b32_e32 v89, v220, v89, vcc
	v_cmp_lt_u32_e32 vcc, s89, v136
	v_add_u32_e32 v136, -13, v204
	s_nop 0
	v_cndmask_b32_e32 v90, v220, v90, vcc
	v_cmp_lt_u32_e32 vcc, s89, v136
	v_add_u32_e32 v136, -8, v204
	s_nop 0
	v_cndmask_b32_e32 v91, v220, v91, vcc
	v_cmp_lt_u32_e32 vcc, s89, v136
	v_add_u32_e32 v136, -7, v204
	s_nop 0
	v_cndmask_b32_e32 v92, v220, v92, vcc
	v_cmp_lt_u32_e32 vcc, s89, v136
	v_add_u32_e32 v136, -6, v204
	s_nop 0
	v_cndmask_b32_e32 v93, v220, v93, vcc
	v_cmp_lt_u32_e32 vcc, s89, v136
	v_add_u32_e32 v136, -5, v204
	s_nop 0
	v_cndmask_b32_e32 v94, v220, v94, vcc
	v_cmp_lt_u32_e32 vcc, s89, v136
	v_add_u32_e32 v136, 1, v204
	s_nop 0
	v_cndmask_b32_e32 v95, v220, v95, vcc
	v_cmp_lt_u32_e32 vcc, s89, v204
	s_nop 1
	v_cndmask_b32_e32 v64, v220, v64, vcc
	v_cmp_lt_u32_e32 vcc, s89, v136
	v_add_u32_e32 v136, 2, v204
	s_nop 0
	v_cndmask_b32_e32 v65, v220, v65, vcc
	v_cmp_lt_u32_e32 vcc, s89, v136
	v_add_u32_e32 v136, 3, v204
	s_nop 0
	v_cndmask_b32_e32 v66, v220, v66, vcc
	v_cmp_lt_u32_e32 vcc, s89, v136
	v_add_u32_e32 v136, 8, v204
	s_nop 0
	v_cndmask_b32_e32 v67, v220, v67, vcc
	v_cmp_lt_u32_e32 vcc, s89, v136
	v_add_u32_e32 v136, 9, v204
	s_nop 0
	v_cndmask_b32_e32 v68, v220, v68, vcc
	v_cmp_lt_u32_e32 vcc, s89, v136
	v_add_u32_e32 v136, 10, v204
	s_nop 0
	v_cndmask_b32_e32 v69, v220, v69, vcc
	v_cmp_lt_u32_e32 vcc, s89, v136
	v_add_u32_e32 v136, 11, v204
	s_nop 0
	v_cndmask_b32_e32 v70, v220, v70, vcc
	v_cmp_lt_u32_e32 vcc, s89, v136
	v_add_u32_e32 v136, 16, v204
	s_nop 0
	v_cndmask_b32_e32 v71, v220, v71, vcc
	v_cmp_lt_u32_e32 vcc, s89, v136
	v_add_u32_e32 v136, 17, v204
	s_nop 0
	v_cndmask_b32_e32 v72, v220, v72, vcc
	v_cmp_lt_u32_e32 vcc, s89, v136
	v_add_u32_e32 v136, 18, v204
	s_nop 0
	v_cndmask_b32_e32 v73, v220, v73, vcc
	v_cmp_lt_u32_e32 vcc, s89, v136
	v_add_u32_e32 v136, 19, v204
	s_nop 0
	v_cndmask_b32_e32 v74, v220, v74, vcc
	v_cmp_lt_u32_e32 vcc, s89, v136
	v_add_u32_e32 v136, 24, v204
	s_nop 0
	v_cndmask_b32_e32 v75, v220, v75, vcc
	v_cmp_lt_u32_e32 vcc, s89, v136
	v_add_u32_e32 v136, 25, v204
	s_nop 0
	v_cndmask_b32_e32 v76, v220, v76, vcc
	v_cmp_lt_u32_e32 vcc, s89, v136
	v_add_u32_e32 v136, 26, v204
	s_nop 0
	v_cndmask_b32_e32 v77, v220, v77, vcc
	v_cmp_lt_u32_e32 vcc, s89, v136
	v_add_u32_e32 v136, 27, v204
	s_nop 0
	v_cndmask_b32_e32 v78, v220, v78, vcc
	v_cmp_lt_u32_e32 vcc, s89, v136
	s_nop 1
	v_cndmask_b32_e32 v79, v220, v79, vcc
.LBB0_357:
	v_add_f32_e32 v136, 0, v206
	v_add_f32_e32 v136, v209, v136
	v_add_f32_e32 v136, v211, v136
	v_add_f32_e32 v136, v213, v136
	v_add_f32_e32 v136, v215, v136
	v_add_f32_e32 v136, v222, v136
	v_add_f32_e32 v136, v223, v136
	v_add_f32_e32 v136, v224, v136
	v_add_f32_e32 v136, v225, v136
	s_nop 0
	v_max_f32_e32 v137, v81, v81
	v_max_f32_e32 v138, v80, v80
	v_add_f32_e32 v136, v226, v136
	v_max_f32_e32 v137, v138, v137
	v_add_f32_e32 v136, v227, v136
	v_max3_f32 v137, v137, v82, v83
	v_add_f32_e32 v136, v228, v136
	v_max3_f32 v137, v137, v84, v85
	v_add_f32_e32 v136, v229, v136
	v_max3_f32 v137, v137, v86, v87
	v_add_f32_e32 v136, v230, v136
	v_max3_f32 v137, v137, v88, v89
	v_add_f32_e32 v136, v231, v136
	v_max3_f32 v137, v137, v90, v91
	v_add_f32_e32 v136, v232, v136
	v_max3_f32 v137, v137, v92, v93
	v_add_f32_e32 v136, v233, v136
	v_max3_f32 v137, v137, v94, v95
	v_add_f32_e32 v136, v234, v136
	v_max3_f32 v137, v137, v64, v65
	v_add_f32_e32 v136, v235, v136
	v_max3_f32 v137, v137, v66, v67
	v_add_f32_e32 v136, v236, v136
	v_max3_f32 v137, v137, v68, v69
	v_add_f32_e32 v136, v237, v136
	v_max3_f32 v137, v137, v70, v71
	v_add_f32_e32 v136, v238, v136
	v_max3_f32 v137, v137, v72, v73
	v_add_f32_e32 v136, v239, v136
	v_max3_f32 v137, v137, v74, v75
	v_add_f32_e32 v136, v240, v136
	v_max3_f32 v137, v137, v76, v77
	v_add_f32_e32 v136, v241, v136
	v_max3_f32 v137, v137, v78, v79
	v_add_f32_e32 v136, v242, v136
	v_mov_b32_e32 v138, v137
	v_add_f32_e32 v136, v243, v136
	v_add_f32_e32 v136, v207, v136
	v_add_f32_e32 v136, v210, v136
	v_add_f32_e32 v136, v212, v136
	v_add_f32_e32 v139, v214, v136
	v_permlane32_swap_b32_e32 v138, v137
	v_max3_f32 v136, v202, v137, v138
	v_sub_f32_e32 v80, v80, v136
	v_exp_f32_e32 v137, v80
	v_sub_f32_e32 v81, v81, v136
	v_exp_f32_e32 v81, v81
	v_sub_f32_e32 v82, v82, v136
	v_exp_f32_e32 v82, v82
	v_sub_f32_e32 v83, v83, v136
	v_exp_f32_e32 v83, v83
	v_sub_f32_e32 v84, v84, v136
	v_add_f32_e32 v80, v208, v139
	v_add_f32_e32 v139, 0, v137
	v_exp_f32_e32 v84, v84
	v_sub_f32_e32 v85, v85, v136
	v_add_f32_e32 v139, v81, v139
; #define LAS __attribute__((address_space(3)))
; __device__ __forceinline__ unsigned cvt_pk_bf16(float lo, float hi) { unsigned r; asm volatile("v_cvt_pk_bf16_f32 %0, %1, %2" : "=v"(r) : "v"(lo), "v"(hi)); return r; }
; __device__ __forceinline__ void attn_unit(LAS unsigned char* lds, const bf16_t* Q, const bf16_t* Kb, const bf16_t* Vb, bf16_t* O, const float* sink,
;                                           int qrow0, int kvh, int crow0, int lrow0, int jlo, int jhi, int qpos0, const int wave_s) {
;     ...
; #pragma unroll
;             for (int kt = 0; kt < 2; ++kt)
; #pragma unroll
;                 for (int r = 0; r < 16; ++r) mx = fmaxf(mx, S[kt][r]);
;             mx = fmaxf(mx, xor_lane(mx, lane, 32));
;             const float mnew = fmaxf(mrow[qs], mx);
;             const float alpha = __builtin_amdgcn_exp2f(mrow[qs] - mnew);
;             mrow[qs] = mnew;
;             float ps = 0.f;
; #pragma unroll
;             for (int kt = 0; kt < 2; ++kt)
; #pragma unroll
;                 for (int r = 0; r < 16; ++r) { S[kt][r] = __builtin_amdgcn_exp2f(S[kt][r] - mnew); ps += S[kt][r]; }
;             lsum[qs] = lsum[qs] * alpha + ps;
; #pragma unroll
;             for (int dh = 0; dh < 2; ++dh)
; #pragma unroll
;                 for (int r = 0; r < 16; ++r) Oacc[qs][dh][r] *= alpha;
; #pragma unroll
;             for (int s = 0; s < 4; ++s) {
;                 const int kt = s >> 1, sp = s & 1;
;                 u32x4 pw; pw.x = cvt_pk_bf16(S[kt][8 * sp + 0], S[kt][8 * sp + 1]); pw.y = cvt_pk_bf16(S[kt][8 * sp + 2], S[kt][8 * sp + 3]);
;                 pw.z = cvt_pk_bf16(S[kt][8 * sp + 4], S[kt][8 * sp + 5]); pw.w = cvt_pk_bf16(S[kt][8 * sp + 6], S[kt][8 * sp + 7]);
;                 const bf16x8 Pf = __builtin_bit_cast(bf16x8, pw);
; #pragma unroll
;                 for (int dh = 0; dh < 2; ++dh) {
;                     const int g1 = (lane >> 4) & 1, li = lane & 15, q4 = li >> 2, p4 = li & 3;
;                     const LAS unsigned char* va = vb + (16 * s + 4 * h + q4) * VSTR + (32 * dh + 16 * g1 + 4 * p4) * 2;
;                     const s16x4 lo = vtr(va), hi = vtr(va + 8 * VSTR);
;                     const bf16x8 Vf = (bf16x8){lo[0], lo[1], lo[2], lo[3], hi[0], hi[1], hi[2], hi[3]};
;                     Oacc[qs][dh] = __builtin_amdgcn_mfma_f32_32x32x16_bf16(Vf, Pf, Oacc[qs][dh], 0, 0, 0);
;                 }
;             }
	v_exp_f32_e32 v85, v85
	v_sub_f32_e32 v86, v86, v136
	v_add_f32_e32 v139, v82, v139
	v_exp_f32_e32 v86, v86
	v_sub_f32_e32 v87, v87, v136
	v_add_f32_e32 v139, v83, v139
	v_exp_f32_e32 v87, v87
	v_sub_f32_e32 v88, v88, v136
	v_add_f32_e32 v139, v84, v139
	v_exp_f32_e32 v88, v88
	v_sub_f32_e32 v89, v89, v136
	v_add_f32_e32 v139, v85, v139
	v_exp_f32_e32 v89, v89
	v_sub_f32_e32 v90, v90, v136
	v_add_f32_e32 v139, v86, v139
	v_exp_f32_e32 v140, v90
	v_sub_f32_e32 v90, v91, v136
	v_add_f32_e32 v139, v87, v139
	v_exp_f32_e32 v91, v90
	v_sub_f32_e32 v90, v92, v136
	v_add_f32_e32 v139, v88, v139
	v_exp_f32_e32 v92, v90
	v_sub_f32_e32 v93, v93, v136
	v_add_f32_e32 v90, v89, v139
	v_exp_f32_e32 v93, v93
	v_sub_f32_e32 v94, v94, v136
	v_add_f32_e32 v90, v140, v90
	v_exp_f32_e32 v94, v94
	v_sub_f32_e32 v95, v95, v136
	v_add_f32_e32 v90, v91, v90
	v_exp_f32_e32 v95, v95
	v_sub_f32_e32 v64, v64, v136
	v_add_f32_e32 v90, v92, v90
	v_exp_f32_e32 v139, v64
	v_sub_f32_e32 v65, v65, v136
	v_add_f32_e32 v64, v93, v90
	v_exp_f32_e32 v141, v65
	v_sub_f32_e32 v65, v66, v136
	v_add_f32_e32 v64, v94, v64
	v_exp_f32_e32 v142, v65
	v_sub_f32_e32 v65, v67, v136
	v_add_f32_e32 v64, v95, v64
	v_exp_f32_e32 v143, v65
	v_sub_f32_e32 v65, v68, v136
	v_add_f32_e32 v64, v139, v64
	v_exp_f32_e32 v144, v65
	v_add_f32_e32 v64, v141, v64
	v_add_f32_e32 v64, v142, v64
	v_add_f32_e32 v64, v143, v64
	v_add_f32_e32 v145, v144, v64
	v_sub_f32_e32 v64, v69, v136
	v_exp_f32_e32 v146, v64
	v_sub_f32_e32 v64, v70, v136
	v_exp_f32_e32 v147, v64
	v_sub_f32_e32 v64, v71, v136
	v_sub_f32_e32 v138, v202, v136
	v_exp_f32_e32 v148, v64
	v_sub_f32_e32 v64, v72, v136
	v_exp_f32_e32 v90, v138
	v_exp_f32_e32 v138, v64
	v_sub_f32_e32 v64, v73, v136
	v_exp_f32_e32 v149, v64
	v_cvt_pk_bf16_f32 v64, v137, v81
	v_cvt_pk_bf16_f32 v65, v82, v83
	v_cvt_pk_bf16_f32 v66, v84, v85
	v_cvt_pk_bf16_f32 v67, v86, v87
	ds_read_b64_tr_b16 v[68:69], v205 offset:18432
	ds_read_b64_tr_b16 v[70:71], v205 offset:19968
	ds_read_b64_tr_b16 v[84:85], v205 offset:20032
	ds_read_b64_tr_b16 v[82:83], v205 offset:18496
	v_pk_mul_f32 v[46:47], v[46:47], v[90:91] op_sel_hi:[1,0]
	v_pk_mul_f32 v[44:45], v[44:45], v[90:91] op_sel_hi:[1,0]
	v_pk_mul_f32 v[42:43], v[42:43], v[90:91] op_sel_hi:[1,0]
	v_pk_mul_f32 v[40:41], v[40:41], v[90:91] op_sel_hi:[1,0]
	v_pk_mul_f32 v[38:39], v[38:39], v[90:91] op_sel_hi:[1,0]
	v_pk_mul_f32 v[36:37], v[36:37], v[90:91] op_sel_hi:[1,0]
	v_pk_mul_f32 v[34:35], v[34:35], v[90:91] op_sel_hi:[1,0]
	v_pk_mul_f32 v[32:33], v[32:33], v[90:91] op_sel_hi:[1,0]
	v_pk_mul_f32 v[30:31], v[30:31], v[90:91] op_sel_hi:[1,0]
	v_pk_mul_f32 v[28:29], v[28:29], v[90:91] op_sel_hi:[1,0]
	v_pk_mul_f32 v[26:27], v[26:27], v[90:91] op_sel_hi:[1,0]
	v_pk_mul_f32 v[24:25], v[24:25], v[90:91] op_sel_hi:[1,0]
	v_pk_mul_f32 v[22:23], v[22:23], v[90:91] op_sel_hi:[1,0]
	v_pk_mul_f32 v[20:21], v[20:21], v[90:91] op_sel_hi:[1,0]
	v_pk_mul_f32 v[18:19], v[18:19], v[90:91] op_sel_hi:[1,0]
	v_pk_mul_f32 v[16:17], v[16:17], v[90:91] op_sel_hi:[1,0]
	s_waitcnt lgkmcnt(2)
	v_mfma_f32_32x32x16_bf16 v[32:47], v[68:71], v[64:67], v[32:47]
	v_cvt_pk_bf16_f32 v68, v88, v89
	v_cvt_pk_bf16_f32 v69, v140, v91
	v_cvt_pk_bf16_f32 v70, v92, v93
	v_cvt_pk_bf16_f32 v71, v94, v95
	ds_read_b64_tr_b16 v[86:87], v205 offset:21504
	ds_read_b64_tr_b16 v[88:89], v205 offset:23040
	v_sub_f32_e32 v72, v76, v136
	v_fmac_f32_e32 v80, v200, v190
	s_waitcnt lgkmcnt(2)
	v_mfma_f32_32x32x16_bf16 v[16:31], v[82:85], v[64:67], v[16:31]
	v_sub_f32_e32 v64, v74, v136
	v_exp_f32_e32 v81, v64
	v_sub_f32_e32 v64, v75, v136
	v_exp_f32_e32 v91, v64
	ds_read_b64_tr_b16 v[66:67], v205 offset:23104
	ds_read_b64_tr_b16 v[64:65], v205 offset:21568
	s_andn2_b64 vcc, exec, s[8:9]
	s_add_i32 s2, s2, 64
	s_waitcnt lgkmcnt(2)
	v_mfma_f32_32x32x16_bf16 v[32:47], v[86:89], v[68:71], v[32:47]
	v_exp_f32_e32 v86, v72
	v_cvt_pk_bf16_f32 v72, v139, v141
	v_cvt_pk_bf16_f32 v73, v142, v143
	v_cvt_pk_bf16_f32 v74, v144, v146
	v_cvt_pk_bf16_f32 v75, v147, v148
	ds_read_b64_tr_b16 v[82:83], v205 offset:24576
	ds_read_b64_tr_b16 v[84:85], v205 offset:26112
	s_waitcnt lgkmcnt(2)
	v_mfma_f32_32x32x16_bf16 v[16:31], v[64:67], v[68:71], v[16:31]
	v_sub_f32_e32 v64, v77, v136
	v_exp_f32_e32 v87, v64
	v_sub_f32_e32 v64, v78, v136
	v_exp_f32_e32 v88, v64
	ds_read_b64_tr_b16 v[66:67], v205 offset:26176
	ds_read_b64_tr_b16 v[64:65], v205 offset:24640
	v_sub_f32_e32 v68, v79, v136
	s_waitcnt lgkmcnt(2)
	v_mfma_f32_32x32x16_bf16 v[32:47], v[82:85], v[72:75], v[32:47]
	v_exp_f32_e32 v82, v68
	v_cvt_pk_bf16_f32 v68, v138, v149
	v_cvt_pk_bf16_f32 v69, v81, v91
	v_cvt_pk_bf16_f32 v70, v86, v87
	v_cvt_pk_bf16_f32 v71, v88, v82
	ds_read_b64_tr_b16 v[76:77], v205 offset:27648
	ds_read_b64_tr_b16 v[78:79], v205 offset:29184
	s_waitcnt lgkmcnt(2)
	v_mfma_f32_32x32x16_bf16 v[16:31], v[64:67], v[72:75], v[16:31]
	ds_read_b64_tr_b16 v[74:75], v205 offset:29248
	ds_read_b64_tr_b16 v[72:73], v205 offset:27712
	v_add_f32_e32 v64, v146, v145
	v_add_f32_e32 v64, v147, v64
	v_add_f32_e32 v64, v148, v64
	v_add_f32_e32 v64, v138, v64
	v_add_f32_e32 v64, v149, v64
	v_add_f32_e32 v64, v81, v64
	s_waitcnt lgkmcnt(2)
	v_mfma_f32_32x32x16_bf16 v[32:47], v[76:79], v[68:71], v[32:47]
	v_add_f32_e32 v64, v91, v64
	v_add_f32_e32 v64, v86, v64
	v_add_f32_e32 v64, v87, v64
	v_add_f32_e32 v64, v88, v64
	v_add_f32_e32 v64, v82, v64
	v_fmac_f32_e32 v64, v201, v90
	s_waitcnt lgkmcnt(0)
	v_mfma_f32_32x32x16_bf16 v[16:31], v[72:75], v[68:71], v[16:31]
	s_cbranch_vccz .LBB0_337
	v_mov_b32_e32 v200, v80
	v_mov_b32_e32 v201, v64
	v_mov_b32_e32 v190, v203
	v_mov_b32_e32 v202, v136
	s_mov_b32 s30, s29
	s_branch .LBB0_347
; __global__ void __launch_bounds__(512, 2) fwd_kernel(const Args a) {
;     ...
;                 const int mend = (l == DEPTH - 1) ? ML : MT;
;                 const float* cw = conv_w + l * 3 * D; const float* cbias = conv_b + l * D;
;                 for (int m = gw; m < mend; m += NGW) {
;                     const bool lat = m < ML; const int t = lat ? (m & (SEQ - 1)) : ((m - ML) & (CTXL - 1)); const int tl = lat ? SEQ - 1 : CTXL - 1;
;                     const bool hp = t > 0, hn = t < tl;
; #pragma unroll
;                     for (int j = 0; j < 4; ++j) {
;                         const int c0 = (64 * j + lane) * 8; const size_t o = (size_t)m * D + c0;
;                         const u32x4 zz = (u32x4){0u, 0u, 0u, 0u};
;                         const u32x4 up = hp ? *(const u32x4*)(Ub + o - D) : zz, uc = *(const u32x4*)(Ub + o), un = hn ? *(const u32x4*)(Ub + o + D) : zz, cb = *(const u32x4*)(CBb + o);
;                         const f32x4 w0a = *(const f32x4*)(cw + c0), w0b = *(const f32x4*)(cw + c0 + 4), w1a = *(const f32x4*)(cw + D + c0), w1b = *(const f32x4*)(cw + D + c0 + 4);
;                         const f32x4 w2a = *(const f32x4*)(cw + 2 * D + c0), w2b = *(const f32x4*)(cw + 2 * D + c0 + 4), ba = *(const f32x4*)(cbias + c0), bb = *(const f32x4*)(cbias + c0 + 4);
.LBB0_359:
	s_and_b64 s[0:1], s[0:1], exec
	s_movk_i32 s0, 0x4200
	s_cselect_b32 s2, 0x4000, s0
	v_readlane_b32 s0, v255, 19
	s_cmp_ge_i32 s0, s2
	v_readlane_b32 s1, v255, 20
	s_cbranch_scc1 .LBB0_379
	s_lshl_b32 s0, s65, 11
	s_ashr_i32 s1, s0, 31
	s_mov_b32 s4, s64
	s_mov_b64 s[10:11], s[66:67]
	s_mov_b32 s8, s65
	s_mov_b32 s9, s68
	s_mov_b32 s12, s69
	s_mov_b32 s13, s70
	s_mov_b64 s[14:15], s[72:73]
	v_readlane_b32 s64, v255, 2
	s_lshl_b64 s[0:1], s[0:1], 2
	v_readlane_b32 s65, v255, 3
	v_readlane_b32 s68, v255, 6
	v_readlane_b32 s69, v255, 7
	s_mov_b32 s65, s8
	s_add_u32 s0, s68, s0
	s_mulk_i32 s8, 0x1800
	s_mov_b32 s68, s9
	s_addc_u32 s1, s69, s1
	s_ashr_i32 s9, s8, 31
	v_readlane_b32 s66, v255, 4
	s_lshl_b64 s[8:9], s[8:9], 2
	v_readlane_b32 s67, v255, 5
	s_add_u32 s8, s66, s8
	s_addc_u32 s9, s67, s9
	s_mov_b64 s[66:67], s[10:11]
	s_add_u32 s10, s8, 0x2000
	s_addc_u32 s11, s9, 0
	v_readlane_b32 s70, v255, 8
	s_mov_b32 s69, s12
	s_add_u32 s12, s8, 0x4000
	v_lshlrev_b32_e32 v176, 5, v188
	s_mov_b32 s70, s13
	s_addc_u32 s13, s9, 0
	v_or_b32_e32 v0, 0x800, v176
	v_mov_b32_e32 v1, v177
	v_lshl_add_u64 v[16:17], s[8:9], 0, v[176:177]
	v_lshl_add_u64 v[18:19], s[10:11], 0, v[176:177]
	v_lshl_add_u64 v[20:21], s[12:13], 0, v[176:177]
	v_lshl_add_u64 v[22:23], s[0:1], 0, v[176:177]
	v_lshl_add_u64 v[24:25], s[10:11], 0, v[0:1]
	v_lshl_add_u64 v[26:27], s[12:13], 0, v[0:1]
	v_or_b32_e32 v0, 0x1000, v176
	v_or_b32_e32 v176, 0x1800, v176
	v_lshl_add_u64 v[34:35], s[0:1], 0, v[0:1]
	v_lshl_add_u64 v[42:43], s[0:1], 0, v[176:177]
	v_readlane_b32 s0, v254, 49
	v_lshl_add_u64 v[36:37], s[8:9], 0, v[176:177]
	v_lshl_add_u64 v[38:39], s[10:11], 0, v[176:177]
	v_lshl_add_u64 v[40:41], s[12:13], 0, v[176:177]
	v_lshlrev_b32_e32 v176, 4, v188
	v_readlane_b32 s1, v254, 50
	v_readlane_b32 s72, v255, 10
	v_readlane_b32 s73, v255, 11
	v_lshl_add_u64 v[44:45], s[0:1], 0, v[176:177]
	v_readlane_b32 s0, v255, 19
	s_mov_b64 s[72:73], s[14:15]
	s_mov_b32 s64, s4
	v_lshl_add_u64 v[28:29], s[8:9], 0, v[0:1]
	v_lshl_add_u64 v[30:31], s[10:11], 0, v[0:1]
	v_lshl_add_u64 v[32:33], s[12:13], 0, v[0:1]
	s_mov_b32 s4, s0
	v_readlane_b32 s71, v255, 9
	v_readlane_b32 s74, v255, 12
	v_readlane_b32 s75, v255, 13
	v_readlane_b32 s76, v255, 14
	v_readlane_b32 s77, v255, 15
	v_readlane_b32 s78, v255, 16
	v_readlane_b32 s79, v255, 17
	v_readlane_b32 s1, v255, 20
	v_readlane_b32 s0, v255, 19
	s_mov_b32 s13, s0
	s_movk_i32 s12, 0x200
	s_cmpk_eq_u32 s2, 0x4200
	s_cbranch_scc0 .Lcv_allwg
	s_cmpk_lt_u32 s0, 0x100
	s_cbranch_scc1 .Lcv_done
	s_sub_u32 s13, s0, 0x100
	s_movk_i32 s12, 0x1c0
.Lcv_allwg:
	s_and_b32 s1, s13, 3
	s_lshr_b32 s4, s13, 2
	s_lshl_b32 s14, s1, 11
	s_mov_b32 s15, 0
	v_lshl_add_u64 v[16:17], v[16:17], 0, s[14:15]
	v_lshl_add_u64 v[18:19], v[18:19], 0, s[14:15]
	v_lshl_add_u64 v[20:21], v[20:21], 0, s[14:15]
	v_lshl_add_u64 v[22:23], v[22:23], 0, s[14:15]
	global_load_dwordx4 v[128:131], v[16:17], off
	global_load_dwordx4 v[132:135], v[16:17], off offset:16
	global_load_dwordx4 v[136:139], v[18:19], off
	global_load_dwordx4 v[140:143], v[18:19], off offset:16
	global_load_dwordx4 v[144:147], v[20:21], off
	global_load_dwordx4 v[148:151], v[20:21], off offset:16
	global_load_dwordx4 v[152:155], v[22:23], off
	global_load_dwordx4 v[156:159], v[22:23], off offset:16
	v_readlane_b32 s8, v254, 49
	v_readlane_b32 s9, v254, 50
	s_lshl_b32 s10, s0, 12
	s_sub_u32 s8, s8, s10
	s_subb_u32 s9, s9, 0
	s_sub_u32 s8, s8, 0x1c00
	s_subb_u32 s9, s9, 0
	s_lshl_b32 s10, s4, 12
	s_lshl_b32 s11, s1, 10
	s_add_u32 s10, s10, s11
	s_add_u32 s8, s8, s10
	s_addc_u32 s9, s9, 0
	v_lshlrev_b32_e32 v0, 4, v188
	v_mov_b32_e32 v1, 0
	v_lshl_add_u64 v[160:161], s[8:9], 0, v[0:1]
	s_sub_u32 s10, s8, 0x4200000
	s_subb_u32 s11, s9, 0
	v_lshl_add_u64 v[164:165], s[10:11], 0, v[0:1]
	v_mov_b32_e32 v166, v164
	v_mov_b32_e32 v167, v165
	s_mov_b64 s[14:15], 0x1000
	v_lshl_add_u64 v[162:163], v[160:161], 0, s[14:15]
	s_lshl_b32 s14, s12, 12
	s_mov_b32 s15, 0
	global_load_dwordx4 v[64:67], v[160:161], off offset:-4096
	global_load_dwordx4 v[68:71], v[160:161], off
	global_load_dwordx4 v[72:75], v[162:163], off
	global_load_dwordx4 v[76:79], v[164:165], off
	v_lshl_add_u64 v[160:161], v[160:161], 0, s[14:15]
	v_lshl_add_u64 v[162:163], v[162:163], 0, s[14:15]
	v_lshl_add_u64 v[164:165], v[164:165], 0, s[14:15]
	global_load_dwordx4 v[80:83], v[160:161], off offset:-4096
	global_load_dwordx4 v[84:87], v[160:161], off
	global_load_dwordx4 v[88:91], v[162:163], off
	global_load_dwordx4 v[92:95], v[164:165], off
	v_lshl_add_u64 v[160:161], v[160:161], 0, s[14:15]
	v_lshl_add_u64 v[162:163], v[162:163], 0, s[14:15]
	v_lshl_add_u64 v[164:165], v[164:165], 0, s[14:15]
	global_load_dwordx4 v[96:99], v[160:161], off offset:-4096
	global_load_dwordx4 v[100:103], v[160:161], off
	global_load_dwordx4 v[104:107], v[162:163], off
	global_load_dwordx4 v[108:111], v[164:165], off
	v_lshl_add_u64 v[160:161], v[160:161], 0, s[14:15]
	v_lshl_add_u64 v[162:163], v[162:163], 0, s[14:15]
	v_lshl_add_u64 v[164:165], v[164:165], 0, s[14:15]
	global_load_dwordx4 v[112:115], v[160:161], off offset:-4096
	global_load_dwordx4 v[116:119], v[160:161], off
	global_load_dwordx4 v[120:123], v[162:163], off
	global_load_dwordx4 v[124:127], v[164:165], off
	v_lshl_add_u64 v[160:161], v[160:161], 0, s[14:15]
	v_lshl_add_u64 v[162:163], v[162:163], 0, s[14:15]
	v_lshl_add_u64 v[164:165], v[164:165], 0, s[14:15]

; __device__ __forceinline__ u32x4 pack8(const f32x4 a, const f32x4 b) { u32x4 w; w.x = cvt_pk_bf16(a[0], a[1]); w.y = cvt_pk_bf16(a[2], a[3]); w.z = cvt_pk_bf16(b[0], b[1]); w.w = cvt_pk_bf16(b[2], b[3]); return w; }
; #define UNPK_LO(q) ((f32x4){bf_lo(q.x), bf_hi(q.x), bf_lo(q.y), bf_hi(q.y)})
; #define UNPK_HI(q) ((f32x4){bf_lo(q.z), bf_hi(q.z), bf_lo(q.w), bf_hi(q.w)})
; __global__ void __launch_bounds__(512, 2) fwd_kernel(const Args a) {
;     ...
;                 for (int m = gw; m < mend; m += NGW) {
;                     const bool lat = m < ML; const int t = lat ? (m & (SEQ - 1)) : ((m - ML) & (CTXL - 1)); const int tl = lat ? SEQ - 1 : CTXL - 1;
;                     const bool hp = t > 0, hn = t < tl;
; #pragma unroll
;                     for (int j = 0; j < 4; ++j) {
;                         const int c0 = (64 * j + lane) * 8; const size_t o = (size_t)m * D + c0;
;                         const u32x4 zz = (u32x4){0u, 0u, 0u, 0u};
;                         const u32x4 up = hp ? *(const u32x4*)(Ub + o - D) : zz, uc = *(const u32x4*)(Ub + o), un = hn ? *(const u32x4*)(Ub + o + D) : zz, cb = *(const u32x4*)(CBb + o);
;                         const f32x4 w0a = *(const f32x4*)(cw + c0), w0b = *(const f32x4*)(cw + c0 + 4), w1a = *(const f32x4*)(cw + D + c0), w1b = *(const f32x4*)(cw + D + c0 + 4);
;                         const f32x4 w2a = *(const f32x4*)(cw + 2 * D + c0), w2b = *(const f32x4*)(cw + 2 * D + c0 + 4), ba = *(const f32x4*)(cbias + c0), bb = *(const f32x4*)(cbias + c0 + 4);
;     ...
;                         const f32x4 ya = UNPK_LO(cb) * (w0a * UNPK_LO(up) + w1a * UNPK_LO(uc) + w2a * UNPK_LO(un) + ba);
;                         const f32x4 yb = UNPK_HI(cb) * (w0b * UNPK_HI(up) + w1b * UNPK_HI(uc) + w2b * UNPK_HI(un) + bb);
;     ...
;                         *(u32x4*)(CBb + o) = pack8(ya, yb);
;                     }
.Lcv_hn0:
	v_lshlrev_b32_e32 v0, 16, v64
	v_and_b32_e32 v1, 0xffff0000, v64
	v_lshlrev_b32_e32 v2, 16, v65
	v_and_b32_e32 v3, 0xffff0000, v65
	v_lshlrev_b32_e32 v4, 16, v66
	v_and_b32_e32 v5, 0xffff0000, v66
	v_lshlrev_b32_e32 v6, 16, v67
	v_and_b32_e32 v7, 0xffff0000, v67
	v_lshlrev_b32_e32 v8, 16, v68
	v_and_b32_e32 v9, 0xffff0000, v68
	v_lshlrev_b32_e32 v10, 16, v69
	v_and_b32_e32 v11, 0xffff0000, v69
	v_lshlrev_b32_e32 v12, 16, v70
	v_and_b32_e32 v13, 0xffff0000, v70
	v_lshlrev_b32_e32 v14, 16, v71
	v_and_b32_e32 v15, 0xffff0000, v71
	v_lshlrev_b32_e32 v16, 16, v72
	v_and_b32_e32 v17, 0xffff0000, v72
	v_lshlrev_b32_e32 v18, 16, v73
	v_and_b32_e32 v19, 0xffff0000, v73
	v_lshlrev_b32_e32 v20, 16, v74
	v_and_b32_e32 v21, 0xffff0000, v74
	v_lshlrev_b32_e32 v22, 16, v75
	v_and_b32_e32 v23, 0xffff0000, v75
	v_lshlrev_b32_e32 v24, 16, v76
	v_and_b32_e32 v25, 0xffff0000, v76
	v_lshlrev_b32_e32 v26, 16, v77
	v_and_b32_e32 v27, 0xffff0000, v77
	v_lshlrev_b32_e32 v28, 16, v78
	v_and_b32_e32 v29, 0xffff0000, v78
	v_lshlrev_b32_e32 v30, 16, v79
	v_and_b32_e32 v31, 0xffff0000, v79
	global_load_dwordx4 v[64:67], v[160:161], off offset:-4096
	global_load_dwordx4 v[68:71], v[160:161], off
	global_load_dwordx4 v[72:75], v[162:163], off
	global_load_dwordx4 v[76:79], v[164:165], off
	v_lshl_add_u64 v[160:161], v[160:161], 0, s[14:15]
	v_lshl_add_u64 v[162:163], v[162:163], 0, s[14:15]
	v_lshl_add_u64 v[164:165], v[164:165], 0, s[14:15]
	v_pk_mul_f32 v[48:49], v[136:137], v[8:9]
	v_pk_fma_f32 v[48:49], v[128:129], v[0:1], v[48:49]
	v_pk_fma_f32 v[48:49], v[144:145], v[16:17], v[48:49]
	v_pk_add_f32 v[48:49], v[152:153], v[48:49]
	v_pk_mul_f32 v[56:57], v[48:49], v[24:25]
	v_pk_mul_f32 v[50:51], v[138:139], v[10:11]
	v_pk_fma_f32 v[50:51], v[130:131], v[2:3], v[50:51]
	v_pk_fma_f32 v[50:51], v[146:147], v[18:19], v[50:51]
	v_pk_add_f32 v[50:51], v[154:155], v[50:51]
	v_pk_mul_f32 v[58:59], v[50:51], v[26:27]
	v_pk_mul_f32 v[52:53], v[140:141], v[12:13]
	v_pk_fma_f32 v[52:53], v[132:133], v[4:5], v[52:53]
	v_pk_fma_f32 v[52:53], v[148:149], v[20:21], v[52:53]
	v_pk_add_f32 v[52:53], v[156:157], v[52:53]
	v_pk_mul_f32 v[60:61], v[52:53], v[28:29]
	v_pk_mul_f32 v[54:55], v[142:143], v[14:15]
	v_pk_fma_f32 v[54:55], v[134:135], v[6:7], v[54:55]
	v_pk_fma_f32 v[54:55], v[150:151], v[22:23], v[54:55]
	v_pk_add_f32 v[54:55], v[158:159], v[54:55]
	v_pk_mul_f32 v[62:63], v[54:55], v[30:31]
	v_cvt_pk_bf16_f32 v32, v56, v57
	v_cvt_pk_bf16_f32 v33, v58, v59
	v_cvt_pk_bf16_f32 v34, v60, v61
	v_cvt_pk_bf16_f32 v35, v62, v63
	global_store_dwordx4 v[166:167], v[32:35], off
	v_lshl_add_u64 v[166:167], v[166:167], 0, s[14:15]
	s_add_u32 s4, s4, s12
	s_cmp_ge_u32 s4, s2
	s_cbranch_scc1 .Lcv_done
	s_movk_i32 s9, 0xff
	s_cmpk_lt_u32 s4, 0x4000
	s_cselect_b32 s8, 0x1fff, s9
	s_and_b32 s9, s4, s8
	s_waitcnt vmcnt(12)
	s_cmp_lg_u32 s9, 0
	s_cbranch_scc1 .Lcv_hp1
	v_mov_b32_e32 v80, 0
	v_mov_b32_e32 v81, 0
	v_mov_b32_e32 v82, 0
	v_mov_b32_e32 v83, 0

; __device__ __forceinline__ u32x4 pack8(const f32x4 a, const f32x4 b) { u32x4 w; w.x = cvt_pk_bf16(a[0], a[1]); w.y = cvt_pk_bf16(a[2], a[3]); w.z = cvt_pk_bf16(b[0], b[1]); w.w = cvt_pk_bf16(b[2], b[3]); return w; }
; #define UNPK_LO(q) ((f32x4){bf_lo(q.x), bf_hi(q.x), bf_lo(q.y), bf_hi(q.y)})
; #define UNPK_HI(q) ((f32x4){bf_lo(q.z), bf_hi(q.z), bf_lo(q.w), bf_hi(q.w)})
; __global__ void __launch_bounds__(512, 2) fwd_kernel(const Args a) {
;     ...
;                 for (int m = gw; m < mend; m += NGW) {
;                     const bool lat = m < ML; const int t = lat ? (m & (SEQ - 1)) : ((m - ML) & (CTXL - 1)); const int tl = lat ? SEQ - 1 : CTXL - 1;
;                     const bool hp = t > 0, hn = t < tl;
; #pragma unroll
;                     for (int j = 0; j < 4; ++j) {
;                         const int c0 = (64 * j + lane) * 8; const size_t o = (size_t)m * D + c0;
;                         const u32x4 zz = (u32x4){0u, 0u, 0u, 0u};
;                         const u32x4 up = hp ? *(const u32x4*)(Ub + o - D) : zz, uc = *(const u32x4*)(Ub + o), un = hn ? *(const u32x4*)(Ub + o + D) : zz, cb = *(const u32x4*)(CBb + o);
;                         const f32x4 w0a = *(const f32x4*)(cw + c0), w0b = *(const f32x4*)(cw + c0 + 4), w1a = *(const f32x4*)(cw + D + c0), w1b = *(const f32x4*)(cw + D + c0 + 4);
;                         const f32x4 w2a = *(const f32x4*)(cw + 2 * D + c0), w2b = *(const f32x4*)(cw + 2 * D + c0 + 4), ba = *(const f32x4*)(cbias + c0), bb = *(const f32x4*)(cbias + c0 + 4);
;     ...
;                         const f32x4 ya = UNPK_LO(cb) * (w0a * UNPK_LO(up) + w1a * UNPK_LO(uc) + w2a * UNPK_LO(un) + ba);
;                         const f32x4 yb = UNPK_HI(cb) * (w0b * UNPK_HI(up) + w1b * UNPK_HI(uc) + w2b * UNPK_HI(un) + bb);
;     ...
;                         *(u32x4*)(CBb + o) = pack8(ya, yb);
;                     }
.Lcv_hn1:
	v_lshlrev_b32_e32 v0, 16, v80
	v_and_b32_e32 v1, 0xffff0000, v80
	v_lshlrev_b32_e32 v2, 16, v81
	v_and_b32_e32 v3, 0xffff0000, v81
	v_lshlrev_b32_e32 v4, 16, v82
	v_and_b32_e32 v5, 0xffff0000, v82
	v_lshlrev_b32_e32 v6, 16, v83
	v_and_b32_e32 v7, 0xffff0000, v83
	v_lshlrev_b32_e32 v8, 16, v84
	v_and_b32_e32 v9, 0xffff0000, v84
	v_lshlrev_b32_e32 v10, 16, v85
	v_and_b32_e32 v11, 0xffff0000, v85
	v_lshlrev_b32_e32 v12, 16, v86
	v_and_b32_e32 v13, 0xffff0000, v86
	v_lshlrev_b32_e32 v14, 16, v87
	v_and_b32_e32 v15, 0xffff0000, v87
	v_lshlrev_b32_e32 v16, 16, v88
	v_and_b32_e32 v17, 0xffff0000, v88
	v_lshlrev_b32_e32 v18, 16, v89
	v_and_b32_e32 v19, 0xffff0000, v89
	v_lshlrev_b32_e32 v20, 16, v90
	v_and_b32_e32 v21, 0xffff0000, v90
	v_lshlrev_b32_e32 v22, 16, v91
	v_and_b32_e32 v23, 0xffff0000, v91
	v_lshlrev_b32_e32 v24, 16, v92
	v_and_b32_e32 v25, 0xffff0000, v92
	v_lshlrev_b32_e32 v26, 16, v93
	v_and_b32_e32 v27, 0xffff0000, v93
	v_lshlrev_b32_e32 v28, 16, v94
	v_and_b32_e32 v29, 0xffff0000, v94
	v_lshlrev_b32_e32 v30, 16, v95
	v_and_b32_e32 v31, 0xffff0000, v95
	global_load_dwordx4 v[80:83], v[160:161], off offset:-4096
	global_load_dwordx4 v[84:87], v[160:161], off
	global_load_dwordx4 v[88:91], v[162:163], off
	global_load_dwordx4 v[92:95], v[164:165], off
	v_lshl_add_u64 v[160:161], v[160:161], 0, s[14:15]
	v_lshl_add_u64 v[162:163], v[162:163], 0, s[14:15]
	v_lshl_add_u64 v[164:165], v[164:165], 0, s[14:15]
	v_pk_mul_f32 v[48:49], v[136:137], v[8:9]
	v_pk_fma_f32 v[48:49], v[128:129], v[0:1], v[48:49]
	v_pk_fma_f32 v[48:49], v[144:145], v[16:17], v[48:49]
	v_pk_add_f32 v[48:49], v[152:153], v[48:49]
	v_pk_mul_f32 v[56:57], v[48:49], v[24:25]
	v_pk_mul_f32 v[50:51], v[138:139], v[10:11]
	v_pk_fma_f32 v[50:51], v[130:131], v[2:3], v[50:51]
	v_pk_fma_f32 v[50:51], v[146:147], v[18:19], v[50:51]
	v_pk_add_f32 v[50:51], v[154:155], v[50:51]
	v_pk_mul_f32 v[58:59], v[50:51], v[26:27]
	v_pk_mul_f32 v[52:53], v[140:141], v[12:13]
	v_pk_fma_f32 v[52:53], v[132:133], v[4:5], v[52:53]
	v_pk_fma_f32 v[52:53], v[148:149], v[20:21], v[52:53]
	v_pk_add_f32 v[52:53], v[156:157], v[52:53]
	v_pk_mul_f32 v[60:61], v[52:53], v[28:29]
	v_pk_mul_f32 v[54:55], v[142:143], v[14:15]
	v_pk_fma_f32 v[54:55], v[134:135], v[6:7], v[54:55]
	v_pk_fma_f32 v[54:55], v[150:151], v[22:23], v[54:55]
	v_pk_add_f32 v[54:55], v[158:159], v[54:55]
	v_pk_mul_f32 v[62:63], v[54:55], v[30:31]
	v_cvt_pk_bf16_f32 v36, v56, v57
	v_cvt_pk_bf16_f32 v37, v58, v59
	v_cvt_pk_bf16_f32 v38, v60, v61
	v_cvt_pk_bf16_f32 v39, v62, v63
	global_store_dwordx4 v[166:167], v[36:39], off
	v_lshl_add_u64 v[166:167], v[166:167], 0, s[14:15]
	s_add_u32 s4, s4, s12
	s_cmp_ge_u32 s4, s2
	s_cbranch_scc1 .Lcv_done
	s_movk_i32 s9, 0xff
	s_cmpk_lt_u32 s4, 0x4000
	s_cselect_b32 s8, 0x1fff, s9
	s_and_b32 s9, s4, s8
	s_waitcnt vmcnt(12)
	s_cmp_lg_u32 s9, 0
	s_cbranch_scc1 .Lcv_hp2
	v_mov_b32_e32 v96, 0
	v_mov_b32_e32 v97, 0
	v_mov_b32_e32 v98, 0
	v_mov_b32_e32 v99, 0

; __device__ __forceinline__ u32x4 pack8(const f32x4 a, const f32x4 b) { u32x4 w; w.x = cvt_pk_bf16(a[0], a[1]); w.y = cvt_pk_bf16(a[2], a[3]); w.z = cvt_pk_bf16(b[0], b[1]); w.w = cvt_pk_bf16(b[2], b[3]); return w; }
; #define UNPK_LO(q) ((f32x4){bf_lo(q.x), bf_hi(q.x), bf_lo(q.y), bf_hi(q.y)})
; #define UNPK_HI(q) ((f32x4){bf_lo(q.z), bf_hi(q.z), bf_lo(q.w), bf_hi(q.w)})
; __global__ void __launch_bounds__(512, 2) fwd_kernel(const Args a) {
;     ...
;                 for (int m = gw; m < mend; m += NGW) {
;                     const bool lat = m < ML; const int t = lat ? (m & (SEQ - 1)) : ((m - ML) & (CTXL - 1)); const int tl = lat ? SEQ - 1 : CTXL - 1;
;                     const bool hp = t > 0, hn = t < tl;
; #pragma unroll
;                     for (int j = 0; j < 4; ++j) {
;                         const int c0 = (64 * j + lane) * 8; const size_t o = (size_t)m * D + c0;
;                         const u32x4 zz = (u32x4){0u, 0u, 0u, 0u};
;                         const u32x4 up = hp ? *(const u32x4*)(Ub + o - D) : zz, uc = *(const u32x4*)(Ub + o), un = hn ? *(const u32x4*)(Ub + o + D) : zz, cb = *(const u32x4*)(CBb + o);
;                         const f32x4 w0a = *(const f32x4*)(cw + c0), w0b = *(const f32x4*)(cw + c0 + 4), w1a = *(const f32x4*)(cw + D + c0), w1b = *(const f32x4*)(cw + D + c0 + 4);
;                         const f32x4 w2a = *(const f32x4*)(cw + 2 * D + c0), w2b = *(const f32x4*)(cw + 2 * D + c0 + 4), ba = *(const f32x4*)(cbias + c0), bb = *(const f32x4*)(cbias + c0 + 4);
;     ...
;                         const f32x4 ya = UNPK_LO(cb) * (w0a * UNPK_LO(up) + w1a * UNPK_LO(uc) + w2a * UNPK_LO(un) + ba);
;                         const f32x4 yb = UNPK_HI(cb) * (w0b * UNPK_HI(up) + w1b * UNPK_HI(uc) + w2b * UNPK_HI(un) + bb);
;     ...
;                         *(u32x4*)(CBb + o) = pack8(ya, yb);
;                     }
.Lcv_hn2:
	v_lshlrev_b32_e32 v0, 16, v96
	v_and_b32_e32 v1, 0xffff0000, v96
	v_lshlrev_b32_e32 v2, 16, v97
	v_and_b32_e32 v3, 0xffff0000, v97
	v_lshlrev_b32_e32 v4, 16, v98
	v_and_b32_e32 v5, 0xffff0000, v98
	v_lshlrev_b32_e32 v6, 16, v99
	v_and_b32_e32 v7, 0xffff0000, v99
	v_lshlrev_b32_e32 v8, 16, v100
	v_and_b32_e32 v9, 0xffff0000, v100
	v_lshlrev_b32_e32 v10, 16, v101
	v_and_b32_e32 v11, 0xffff0000, v101
	v_lshlrev_b32_e32 v12, 16, v102
	v_and_b32_e32 v13, 0xffff0000, v102
	v_lshlrev_b32_e32 v14, 16, v103
	v_and_b32_e32 v15, 0xffff0000, v103
	v_lshlrev_b32_e32 v16, 16, v104
	v_and_b32_e32 v17, 0xffff0000, v104
	v_lshlrev_b32_e32 v18, 16, v105
	v_and_b32_e32 v19, 0xffff0000, v105
	v_lshlrev_b32_e32 v20, 16, v106
	v_and_b32_e32 v21, 0xffff0000, v106
	v_lshlrev_b32_e32 v22, 16, v107
	v_and_b32_e32 v23, 0xffff0000, v107
	v_lshlrev_b32_e32 v24, 16, v108
	v_and_b32_e32 v25, 0xffff0000, v108
	v_lshlrev_b32_e32 v26, 16, v109
	v_and_b32_e32 v27, 0xffff0000, v109
	v_lshlrev_b32_e32 v28, 16, v110
	v_and_b32_e32 v29, 0xffff0000, v110
	v_lshlrev_b32_e32 v30, 16, v111
	v_and_b32_e32 v31, 0xffff0000, v111
	global_load_dwordx4 v[96:99], v[160:161], off offset:-4096
	global_load_dwordx4 v[100:103], v[160:161], off
	global_load_dwordx4 v[104:107], v[162:163], off
	global_load_dwordx4 v[108:111], v[164:165], off
	v_lshl_add_u64 v[160:161], v[160:161], 0, s[14:15]
	v_lshl_add_u64 v[162:163], v[162:163], 0, s[14:15]
	v_lshl_add_u64 v[164:165], v[164:165], 0, s[14:15]
	v_pk_mul_f32 v[48:49], v[136:137], v[8:9]
	v_pk_fma_f32 v[48:49], v[128:129], v[0:1], v[48:49]
	v_pk_fma_f32 v[48:49], v[144:145], v[16:17], v[48:49]
	v_pk_add_f32 v[48:49], v[152:153], v[48:49]
	v_pk_mul_f32 v[56:57], v[48:49], v[24:25]
	v_pk_mul_f32 v[50:51], v[138:139], v[10:11]
	v_pk_fma_f32 v[50:51], v[130:131], v[2:3], v[50:51]
	v_pk_fma_f32 v[50:51], v[146:147], v[18:19], v[50:51]
	v_pk_add_f32 v[50:51], v[154:155], v[50:51]
	v_pk_mul_f32 v[58:59], v[50:51], v[26:27]
	v_pk_mul_f32 v[52:53], v[140:141], v[12:13]
	v_pk_fma_f32 v[52:53], v[132:133], v[4:5], v[52:53]
	v_pk_fma_f32 v[52:53], v[148:149], v[20:21], v[52:53]
	v_pk_add_f32 v[52:53], v[156:157], v[52:53]
	v_pk_mul_f32 v[60:61], v[52:53], v[28:29]
	v_pk_mul_f32 v[54:55], v[142:143], v[14:15]
	v_pk_fma_f32 v[54:55], v[134:135], v[6:7], v[54:55]
	v_pk_fma_f32 v[54:55], v[150:151], v[22:23], v[54:55]
	v_pk_add_f32 v[54:55], v[158:159], v[54:55]
	v_pk_mul_f32 v[62:63], v[54:55], v[30:31]
	v_cvt_pk_bf16_f32 v40, v56, v57
	v_cvt_pk_bf16_f32 v41, v58, v59
	v_cvt_pk_bf16_f32 v42, v60, v61
	v_cvt_pk_bf16_f32 v43, v62, v63
	global_store_dwordx4 v[166:167], v[40:43], off
	v_lshl_add_u64 v[166:167], v[166:167], 0, s[14:15]
	s_add_u32 s4, s4, s12
	s_cmp_ge_u32 s4, s2
	s_cbranch_scc1 .Lcv_done
	s_movk_i32 s9, 0xff
	s_cmpk_lt_u32 s4, 0x4000
	s_cselect_b32 s8, 0x1fff, s9
	s_and_b32 s9, s4, s8
	s_waitcnt vmcnt(12)
	s_cmp_lg_u32 s9, 0
	s_cbranch_scc1 .Lcv_hp3
	v_mov_b32_e32 v112, 0
	v_mov_b32_e32 v113, 0
	v_mov_b32_e32 v114, 0
	v_mov_b32_e32 v115, 0

; __device__ __forceinline__ u32x4 pack8(const f32x4 a, const f32x4 b) { u32x4 w; w.x = cvt_pk_bf16(a[0], a[1]); w.y = cvt_pk_bf16(a[2], a[3]); w.z = cvt_pk_bf16(b[0], b[1]); w.w = cvt_pk_bf16(b[2], b[3]); return w; }
; #define UNPK_LO(q) ((f32x4){bf_lo(q.x), bf_hi(q.x), bf_lo(q.y), bf_hi(q.y)})
; #define UNPK_HI(q) ((f32x4){bf_lo(q.z), bf_hi(q.z), bf_lo(q.w), bf_hi(q.w)})
; __global__ void __launch_bounds__(512, 2) fwd_kernel(const Args a) {
;     ...
;                 for (int m = gw; m < mend; m += NGW) {
;                     const bool lat = m < ML; const int t = lat ? (m & (SEQ - 1)) : ((m - ML) & (CTXL - 1)); const int tl = lat ? SEQ - 1 : CTXL - 1;
;                     const bool hp = t > 0, hn = t < tl;
; #pragma unroll
;                     for (int j = 0; j < 4; ++j) {
;                         const int c0 = (64 * j + lane) * 8; const size_t o = (size_t)m * D + c0;
;                         const u32x4 zz = (u32x4){0u, 0u, 0u, 0u};
;                         const u32x4 up = hp ? *(const u32x4*)(Ub + o - D) : zz, uc = *(const u32x4*)(Ub + o), un = hn ? *(const u32x4*)(Ub + o + D) : zz, cb = *(const u32x4*)(CBb + o);
;                         const f32x4 w0a = *(const f32x4*)(cw + c0), w0b = *(const f32x4*)(cw + c0 + 4), w1a = *(const f32x4*)(cw + D + c0), w1b = *(const f32x4*)(cw + D + c0 + 4);
;                         const f32x4 w2a = *(const f32x4*)(cw + 2 * D + c0), w2b = *(const f32x4*)(cw + 2 * D + c0 + 4), ba = *(const f32x4*)(cbias + c0), bb = *(const f32x4*)(cbias + c0 + 4);
;     ...
;                         const f32x4 ya = UNPK_LO(cb) * (w0a * UNPK_LO(up) + w1a * UNPK_LO(uc) + w2a * UNPK_LO(un) + ba);
;                         const f32x4 yb = UNPK_HI(cb) * (w0b * UNPK_HI(up) + w1b * UNPK_HI(uc) + w2b * UNPK_HI(un) + bb);
;     ...
;                         *(u32x4*)(CBb + o) = pack8(ya, yb);
;                     }
.Lcv_hn3:
	v_lshlrev_b32_e32 v0, 16, v112
	v_and_b32_e32 v1, 0xffff0000, v112
	v_lshlrev_b32_e32 v2, 16, v113
	v_and_b32_e32 v3, 0xffff0000, v113
	v_lshlrev_b32_e32 v4, 16, v114
	v_and_b32_e32 v5, 0xffff0000, v114
	v_lshlrev_b32_e32 v6, 16, v115
	v_and_b32_e32 v7, 0xffff0000, v115
	v_lshlrev_b32_e32 v8, 16, v116
	v_and_b32_e32 v9, 0xffff0000, v116
	v_lshlrev_b32_e32 v10, 16, v117
	v_and_b32_e32 v11, 0xffff0000, v117
	v_lshlrev_b32_e32 v12, 16, v118
	v_and_b32_e32 v13, 0xffff0000, v118
	v_lshlrev_b32_e32 v14, 16, v119
	v_and_b32_e32 v15, 0xffff0000, v119
	v_lshlrev_b32_e32 v16, 16, v120
	v_and_b32_e32 v17, 0xffff0000, v120
	v_lshlrev_b32_e32 v18, 16, v121
	v_and_b32_e32 v19, 0xffff0000, v121
	v_lshlrev_b32_e32 v20, 16, v122
	v_and_b32_e32 v21, 0xffff0000, v122
	v_lshlrev_b32_e32 v22, 16, v123
	v_and_b32_e32 v23, 0xffff0000, v123
	v_lshlrev_b32_e32 v24, 16, v124
	v_and_b32_e32 v25, 0xffff0000, v124
	v_lshlrev_b32_e32 v26, 16, v125
	v_and_b32_e32 v27, 0xffff0000, v125
	v_lshlrev_b32_e32 v28, 16, v126
	v_and_b32_e32 v29, 0xffff0000, v126
	v_lshlrev_b32_e32 v30, 16, v127
	v_and_b32_e32 v31, 0xffff0000, v127
	global_load_dwordx4 v[112:115], v[160:161], off offset:-4096
	global_load_dwordx4 v[116:119], v[160:161], off
	global_load_dwordx4 v[120:123], v[162:163], off
	global_load_dwordx4 v[124:127], v[164:165], off
	v_lshl_add_u64 v[160:161], v[160:161], 0, s[14:15]
	v_lshl_add_u64 v[162:163], v[162:163], 0, s[14:15]
	v_lshl_add_u64 v[164:165], v[164:165], 0, s[14:15]
	v_pk_mul_f32 v[48:49], v[136:137], v[8:9]
	v_pk_fma_f32 v[48:49], v[128:129], v[0:1], v[48:49]
	v_pk_fma_f32 v[48:49], v[144:145], v[16:17], v[48:49]
	v_pk_add_f32 v[48:49], v[152:153], v[48:49]
	v_pk_mul_f32 v[56:57], v[48:49], v[24:25]
	v_pk_mul_f32 v[50:51], v[138:139], v[10:11]
	v_pk_fma_f32 v[50:51], v[130:131], v[2:3], v[50:51]
	v_pk_fma_f32 v[50:51], v[146:147], v[18:19], v[50:51]
	v_pk_add_f32 v[50:51], v[154:155], v[50:51]
	v_pk_mul_f32 v[58:59], v[50:51], v[26:27]
	v_pk_mul_f32 v[52:53], v[140:141], v[12:13]
	v_pk_fma_f32 v[52:53], v[132:133], v[4:5], v[52:53]
	v_pk_fma_f32 v[52:53], v[148:149], v[20:21], v[52:53]
	v_pk_add_f32 v[52:53], v[156:157], v[52:53]
	v_pk_mul_f32 v[60:61], v[52:53], v[28:29]
	v_pk_mul_f32 v[54:55], v[142:143], v[14:15]
	v_pk_fma_f32 v[54:55], v[134:135], v[6:7], v[54:55]
	v_pk_fma_f32 v[54:55], v[150:151], v[22:23], v[54:55]
	v_pk_add_f32 v[54:55], v[158:159], v[54:55]
	v_pk_mul_f32 v[62:63], v[54:55], v[30:31]
	v_cvt_pk_bf16_f32 v44, v56, v57
	v_cvt_pk_bf16_f32 v45, v58, v59
	v_cvt_pk_bf16_f32 v46, v60, v61
	v_cvt_pk_bf16_f32 v47, v62, v63
	global_store_dwordx4 v[166:167], v[44:47], off
	v_lshl_add_u64 v[166:167], v[166:167], 0, s[14:15]
	s_add_u32 s4, s4, s12
	s_branch .Lcv_loop
